# GEMM K loop: stage DMAs issued later in the MFMA stream (behind MFMA 8,12,16,20,24,28)
# speedup vs baseline: 1.0028x; 1.0028x over previous
.LBB0_246:
	s_add_i32 s10, s7, 0xffffa000
	s_cmp_lg_u32 s7, 0
	s_cselect_b32 s12, s10, 0xc000
	v_add_u32_e32 v131, s7, v150
	s_waitcnt vmcnt(6)
	s_barrier
	v_add_u32_e32 v133, s7, v149
	ds_read_b128 v[154:157], v131 offset:0
	ds_read_b128 v[158:161], v131 offset:0x400
	ds_read_b128 v[162:165], v131 offset:0x800
	ds_read_b128 v[166:169], v131 offset:0xc00
	v_add_u32_e32 v131, s12, v147
	ds_read_b128 v[170:173], v133 offset:0
	ds_read_b128 v[174:177], v133 offset:0x400
	ds_read_b128 v[178:181], v133 offset:0x800
	ds_read_b128 v[200:203], v133 offset:0xc00
	ds_read_b128 v[204:207], v133 offset:0x1000
	ds_read_b128 v[208:211], v133 offset:0x1400
	ds_read_b128 v[212:215], v133 offset:0x1800
	ds_read_b128 v[216:219], v133 offset:0x1c00
	s_add_u32 s10, s8, s50
	s_addc_u32 s11, s9, s51
	v_readfirstlane_b32 s13, v131
	s_add_u32 s64, s5, s100
	s_addc_u32 s65, s6, 0
	s_add_i32 s66, s7, 0x6000
	s_cmpk_lg_u32 s7, 0xc000
	s_cselect_b32 s7, s66, 0
	s_addk_i32 s100, 0x400
	s_add_u32 s50, s50, s60
	s_addc_u32 s51, s51, 0
	s_sub_i32 s68, s13, s12
	s_lshr_b32 s68, s68, 1
	s_add_i32 s68, s68, s12
	s_addk_i32 s68, 0x4000
	s_waitcnt lgkmcnt(4)
	v_mfma_f32_16x16x32_bf16 v[126:129], v[154:157], v[170:173], v[126:129]
	v_mfma_f32_16x16x32_bf16 v[122:125], v[154:157], v[174:177], v[122:125]
	v_mfma_f32_16x16x32_bf16 v[118:121], v[154:157], v[178:181], v[118:121]
	v_mfma_f32_16x16x32_bf16 v[114:117], v[154:157], v[200:203], v[114:117]
	v_mfma_f32_16x16x32_bf16 v[110:113], v[158:161], v[170:173], v[110:113]
	v_mfma_f32_16x16x32_bf16 v[102:105], v[158:161], v[174:177], v[102:105]
	v_mfma_f32_16x16x32_bf16 v[94:97], v[158:161], v[178:181], v[94:97]
	s_mov_b32 m0, s13
	v_mfma_f32_16x16x32_bf16 v[86:89], v[158:161], v[200:203], v[86:89]
	global_load_lds_dwordx4 v0, s[10:11]
	v_mfma_f32_16x16x32_bf16 v[78:81], v[162:165], v[170:173], v[78:81]
	v_mfma_f32_16x16x32_bf16 v[70:73], v[162:165], v[174:177], v[70:73]
	v_mfma_f32_16x16x32_bf16 v[62:65], v[162:165], v[178:181], v[62:65]
	s_add_u32 m0, s13, 0x400
	v_mfma_f32_16x16x32_bf16 v[54:57], v[162:165], v[200:203], v[54:57]
	global_load_lds_dwordx4 v130, s[10:11]
	v_mfma_f32_16x16x32_bf16 v[46:49], v[166:169], v[170:173], v[46:49]
	v_mfma_f32_16x16x32_bf16 v[38:41], v[166:169], v[174:177], v[38:41]
	v_mfma_f32_16x16x32_bf16 v[30:33], v[166:169], v[178:181], v[30:33]
	s_add_u32 m0, s13, 0x800
	v_mfma_f32_16x16x32_bf16 v[22:25], v[166:169], v[200:203], v[22:25]
	global_load_lds_dwordx4 v132, s[10:11]
	s_waitcnt lgkmcnt(0)
	v_mfma_f32_16x16x32_bf16 v[106:109], v[154:157], v[204:207], v[106:109]
	v_mfma_f32_16x16x32_bf16 v[98:101], v[154:157], v[208:211], v[98:101]
	v_mfma_f32_16x16x32_bf16 v[90:93], v[154:157], v[212:215], v[90:93]
	s_add_u32 m0, s13, 0xc00
	v_mfma_f32_16x16x32_bf16 v[82:85], v[154:157], v[216:219], v[82:85]
	global_load_lds_dwordx4 v136, s[10:11]
	v_mfma_f32_16x16x32_bf16 v[74:77], v[158:161], v[204:207], v[74:77]
	v_mfma_f32_16x16x32_bf16 v[66:69], v[158:161], v[208:211], v[66:69]
	v_mfma_f32_16x16x32_bf16 v[58:61], v[158:161], v[212:215], v[58:61]
	s_mov_b32 m0, s68
	v_mfma_f32_16x16x32_bf16 v[50:53], v[158:161], v[216:219], v[50:53]
	global_load_lds_dwordx4 v138, s[64:65]
	v_mfma_f32_16x16x32_bf16 v[42:45], v[162:165], v[204:207], v[42:45]
	v_mfma_f32_16x16x32_bf16 v[34:37], v[162:165], v[208:211], v[34:37]
	v_mfma_f32_16x16x32_bf16 v[26:29], v[162:165], v[212:215], v[26:29]
	s_add_u32 m0, s68, 0x400
	v_mfma_f32_16x16x32_bf16 v[18:21], v[162:165], v[216:219], v[18:21]
	global_load_lds_dwordx4 v140, s[64:65]
	v_mfma_f32_16x16x32_bf16 v[14:17], v[166:169], v[204:207], v[14:17]
	v_mfma_f32_16x16x32_bf16 v[10:13], v[166:169], v[208:211], v[10:13]
	v_mfma_f32_16x16x32_bf16 v[6:9], v[166:169], v[212:215], v[6:9]
	v_mfma_f32_16x16x32_bf16 v[2:5], v[166:169], v[216:219], v[2:5]
	s_cmpk_lg_i32 s100, 0x7800
	s_cbranch_scc1 .LBB0_246
	s_waitcnt vmcnt(6)
	s_barrier
	v_add_u32_e32 v0, s7, v150
	v_add_u32_e32 v140, s7, v149
	ds_read_b128 v[130:133], v0 offset:0
	ds_read_b128 v[136:139], v0 offset:0x400
	ds_read_b128 v[154:157], v0 offset:0x800
	ds_read_b128 v[158:161], v0 offset:0xc00
	ds_read_b128 v[162:165], v140 offset:0
	ds_read_b128 v[166:169], v140 offset:0x400
	ds_read_b128 v[170:173], v140 offset:0x800
	ds_read_b128 v[174:177], v140 offset:0xc00
	ds_read_b128 v[178:181], v140 offset:0x1000
	ds_read_b128 v[200:203], v140 offset:0x1400
	ds_read_b128 v[204:207], v140 offset:0x1800
	ds_read_b128 v[208:211], v140 offset:0x1c00
	s_lshl_b32 s49, s4, 8
	s_waitcnt lgkmcnt(4)
	s_nop 0
	v_mfma_f32_16x16x32_bf16 v[126:129], v[130:133], v[162:165], v[126:129]
	v_mfma_f32_16x16x32_bf16 v[118:121], v[130:133], v[170:173], v[118:121]
	v_mfma_f32_16x16x32_bf16 v[114:117], v[130:133], v[174:177], v[114:117]
	v_mfma_f32_16x16x32_bf16 v[110:113], v[136:139], v[162:165], v[110:113]
	v_mfma_f32_16x16x32_bf16 v[102:105], v[136:139], v[166:169], v[102:105]
	v_mfma_f32_16x16x32_bf16 v[94:97], v[136:139], v[170:173], v[94:97]
	v_mfma_f32_16x16x32_bf16 v[86:89], v[136:139], v[174:177], v[86:89]
	v_mfma_f32_16x16x32_bf16 v[70:73], v[154:157], v[166:169], v[70:73]
	v_mfma_f32_16x16x32_bf16 v[62:65], v[154:157], v[170:173], v[62:65]
	v_mfma_f32_16x16x32_bf16 v[54:57], v[154:157], v[174:177], v[54:57]
	v_mfma_f32_16x16x32_bf16 v[46:49], v[158:161], v[162:165], v[46:49]
	v_mfma_f32_16x16x32_bf16 v[38:41], v[158:161], v[166:169], v[38:41]
	v_mfma_f32_16x16x32_bf16 v[30:33], v[158:161], v[170:173], v[30:33]
	v_mfma_f32_16x16x32_bf16 v[22:25], v[158:161], v[174:177], v[22:25]
	v_mfma_f32_16x16x32_bf16 v[212:215], v[130:133], v[166:169], v[122:125]
	v_mfma_f32_16x16x32_bf16 v[216:219], v[154:157], v[162:165], v[78:81]
	s_waitcnt lgkmcnt(0)
	s_nop 0
	v_mfma_f32_16x16x32_bf16 v[174:177], v[136:139], v[178:181], v[74:77]
	v_mfma_f32_16x16x32_bf16 v[220:223], v[136:139], v[200:203], v[66:69]
	v_mfma_f32_16x16x32_bf16 v[224:227], v[136:139], v[204:207], v[58:61]
	v_mfma_f32_16x16x32_bf16 v[50:53], v[136:139], v[208:211], v[50:53]
	v_mfma_f32_16x16x32_bf16 v[136:139], v[154:157], v[178:181], v[42:45]
	v_mfma_f32_16x16x32_bf16 v[34:37], v[154:157], v[200:203], v[34:37]
	v_mfma_f32_16x16x32_bf16 v[6:9], v[158:161], v[204:207], v[6:9]
	v_mfma_f32_16x16x32_bf16 v[162:165], v[130:133], v[178:181], v[106:109]
	v_mfma_f32_16x16x32_bf16 v[166:169], v[130:133], v[200:203], v[98:101]
	v_mfma_f32_16x16x32_bf16 v[170:173], v[130:133], v[204:207], v[90:93]
	v_mfma_f32_16x16x32_bf16 v[130:133], v[130:133], v[208:211], v[82:85]
	v_mfma_f32_16x16x32_bf16 v[228:231], v[154:157], v[204:207], v[26:29]
	v_mfma_f32_16x16x32_bf16 v[154:157], v[154:157], v[208:211], v[18:21]
	v_mfma_f32_16x16x32_bf16 v[178:181], v[158:161], v[178:181], v[14:17]
	v_mfma_f32_16x16x32_bf16 v[200:203], v[158:161], v[200:203], v[10:13]
	v_mfma_f32_16x16x32_bf16 v[158:161], v[158:161], v[208:211], v[2:5]
	s_waitcnt vmcnt(0)
	s_barrier
	ds_read_b128 v[2:5], v151 offset:0
	ds_read_b128 v[14:17], v151 offset:0x400
	ds_read_b128 v[204:207], v151 offset:0x800
	ds_read_b128 v[208:211], v151 offset:0xc00
	ds_read_b128 v[10:13], v152 offset:0
	ds_read_b128 v[18:21], v152 offset:0x400
	ds_read_b128 v[26:29], v152 offset:0x800
	ds_read_b128 v[42:45], v152 offset:0xc00
	ds_read_b128 v[232:235], v152 offset:0x1000
	ds_read_b128 v[236:239], v152 offset:0x1400
	ds_read_b128 v[240:243], v152 offset:0x1800
	ds_read_b128 v[244:247], v152 offset:0x1c00
	s_nop 0
	s_waitcnt lgkmcnt(4)
	s_nop 0
	v_mfma_f32_16x16x32_bf16 v[122:125], v[2:5], v[10:13], v[126:129]
	v_mfma_f32_16x16x32_bf16 v[106:109], v[2:5], v[18:21], v[212:215]
	v_mfma_f32_16x16x32_bf16 v[90:93], v[2:5], v[26:29], v[118:121]
	v_mfma_f32_16x16x32_bf16 v[74:77], v[2:5], v[42:45], v[114:117]
	v_mfma_f32_16x16x32_bf16 v[126:129], v[14:17], v[10:13], v[110:113]
	v_mfma_f32_16x16x32_bf16 v[110:113], v[14:17], v[18:21], v[102:105]
	v_mfma_f32_16x16x32_bf16 v[94:97], v[14:17], v[26:29], v[94:97]
	v_mfma_f32_16x16x32_bf16 v[78:81], v[14:17], v[42:45], v[86:89]
	v_mfma_f32_16x16x32_bf16 v[114:117], v[204:207], v[10:13], v[216:219]
	v_mfma_f32_16x16x32_bf16 v[98:101], v[204:207], v[18:21], v[70:73]
	v_mfma_f32_16x16x32_bf16 v[82:85], v[204:207], v[26:29], v[62:65]
	v_mfma_f32_16x16x32_bf16 v[66:69], v[204:207], v[42:45], v[54:57]
	v_mfma_f32_16x16x32_bf16 v[118:121], v[208:211], v[10:13], v[46:49]
	v_mfma_f32_16x16x32_bf16 v[102:105], v[208:211], v[18:21], v[38:41]
	v_mfma_f32_16x16x32_bf16 v[86:89], v[208:211], v[26:29], v[30:33]
	v_mfma_f32_16x16x32_bf16 v[70:73], v[208:211], v[42:45], v[22:25]
	s_waitcnt lgkmcnt(0)
	s_nop 0
	v_mfma_f32_16x16x32_bf16 v[58:61], v[2:5], v[232:235], v[162:165]
	v_mfma_f32_16x16x32_bf16 v[42:45], v[2:5], v[236:239], v[166:169]
	v_mfma_f32_16x16x32_bf16 v[26:29], v[2:5], v[240:243], v[170:173]
	v_mfma_f32_16x16x32_bf16 v[10:13], v[2:5], v[244:247], v[130:133]
	v_mfma_f32_16x16x32_bf16 v[62:65], v[14:17], v[232:235], v[174:177]
	v_mfma_f32_16x16x32_bf16 v[46:49], v[14:17], v[236:239], v[220:223]
	v_mfma_f32_16x16x32_bf16 v[30:33], v[14:17], v[240:243], v[224:227]
	v_mfma_f32_16x16x32_bf16 v[14:17], v[14:17], v[244:247], v[50:53]
	v_mfma_f32_16x16x32_bf16 v[50:53], v[204:207], v[232:235], v[136:139]
	v_mfma_f32_16x16x32_bf16 v[34:37], v[204:207], v[236:239], v[34:37]
	v_mfma_f32_16x16x32_bf16 v[18:21], v[204:207], v[240:243], v[228:231]
	v_mfma_f32_16x16x32_bf16 v[2:5], v[204:207], v[244:247], v[154:157]
	v_mfma_f32_16x16x32_bf16 v[54:57], v[208:211], v[232:235], v[178:181]
	v_mfma_f32_16x16x32_bf16 v[38:41], v[208:211], v[236:239], v[200:203]
	v_mfma_f32_16x16x32_bf16 v[22:25], v[208:211], v[240:243], v[6:9]
	v_mfma_f32_16x16x32_bf16 v[6:9], v[208:211], v[244:247], v[158:161]
	v_mov_b32_e32 v136, v134
	s_mov_b64 s[50:51], -1
	s_and_b64 vcc, exec, s[22:23]
	s_barrier
	s_cbranch_vccz .LBB0_264
	s_and_b64 vcc, exec, s[0:1]
	s_cbranch_vccz .LBB0_250
	v_lshrrev_b32_e32 v0, 6, v136
	v_mul_lo_u32 v137, v0, s14
	v_and_b32_e32 v130, 15, v136
	v_and_or_b32 v0, v136, 48, v137
	s_movk_i32 s4, 0x90
	v_mad_u32_u24 v0, v130, s4, v0
	v_cvt_pk_bf16_f32 v130, v122, v123
	v_cvt_pk_bf16_f32 v131, v124, v125
	v_cvt_pk_bf16_f32 v132, v126, v127
	v_cvt_pk_bf16_f32 v133, v128, v129
	s_waitcnt vmcnt(0)
	ds_write_b128 v0, v[130:133]
	v_cvt_pk_bf16_f32 v130, v114, v115
	v_cvt_pk_bf16_f32 v131, v116, v117
	v_cvt_pk_bf16_f32 v132, v118, v119
	v_cvt_pk_bf16_f32 v133, v120, v121
	ds_write_b128 v0, v[130:133] offset:64
	v_cvt_pk_bf16_f32 v130, v106, v107
	v_cvt_pk_bf16_f32 v131, v108, v109
	v_cvt_pk_bf16_f32 v132, v110, v111
	v_cvt_pk_bf16_f32 v133, v112, v113
	ds_write_b128 v0, v[130:133] offset:2304
	v_cvt_pk_bf16_f32 v130, v98, v99
	v_cvt_pk_bf16_f32 v131, v100, v101
	v_cvt_pk_bf16_f32 v132, v102, v103
	v_cvt_pk_bf16_f32 v133, v104, v105
	ds_write_b128 v0, v[130:133] offset:2368
	v_cvt_pk_bf16_f32 v130, v90, v91
	v_cvt_pk_bf16_f32 v131, v92, v93
	v_cvt_pk_bf16_f32 v132, v94, v95
	v_cvt_pk_bf16_f32 v133, v96, v97
	ds_write_b128 v0, v[130:133] offset:4608
	v_cvt_pk_bf16_f32 v130, v82, v83
	v_cvt_pk_bf16_f32 v131, v84, v85
	v_cvt_pk_bf16_f32 v132, v86, v87
	v_cvt_pk_bf16_f32 v133, v88, v89
	ds_write_b128 v0, v[130:133] offset:4672
	v_cvt_pk_bf16_f32 v130, v74, v75
	v_cvt_pk_bf16_f32 v131, v76, v77
	v_cvt_pk_bf16_f32 v132, v78, v79
	v_cvt_pk_bf16_f32 v133, v80, v81
	ds_write_b128 v0, v[130:133] offset:6912
	v_cvt_pk_bf16_f32 v130, v66, v67
	v_cvt_pk_bf16_f32 v131, v68, v69
	v_cvt_pk_bf16_f32 v132, v70, v71
	v_cvt_pk_bf16_f32 v133, v72, v73
	ds_write_b128 v0, v[130:133] offset:6976
	v_cvt_pk_bf16_f32 v130, v58, v59
	v_cvt_pk_bf16_f32 v131, v60, v61
	v_cvt_pk_bf16_f32 v132, v62, v63
	v_cvt_pk_bf16_f32 v133, v64, v65
	ds_write_b128 v0, v[130:133] offset:9216
	v_cvt_pk_bf16_f32 v130, v50, v51
	v_cvt_pk_bf16_f32 v131, v52, v53
	v_cvt_pk_bf16_f32 v132, v54, v55
	v_cvt_pk_bf16_f32 v133, v56, v57
	ds_write_b128 v0, v[130:133] offset:9280
	v_cvt_pk_bf16_f32 v130, v42, v43
	v_cvt_pk_bf16_f32 v131, v44, v45
	v_cvt_pk_bf16_f32 v132, v46, v47
	v_cvt_pk_bf16_f32 v133, v48, v49
	ds_write_b128 v0, v[130:133] offset:11520
	v_cvt_pk_bf16_f32 v130, v34, v35
	v_cvt_pk_bf16_f32 v131, v36, v37
	v_cvt_pk_bf16_f32 v132, v38, v39
	v_cvt_pk_bf16_f32 v133, v40, v41
	ds_write_b128 v0, v[130:133] offset:11584
	v_cvt_pk_bf16_f32 v130, v26, v27
	v_cvt_pk_bf16_f32 v131, v28, v29
	v_cvt_pk_bf16_f32 v132, v30, v31
	v_cvt_pk_bf16_f32 v133, v32, v33
	ds_write_b128 v0, v[130:133] offset:13824
	v_cvt_pk_bf16_f32 v130, v18, v19
	v_cvt_pk_bf16_f32 v131, v20, v21
	v_cvt_pk_bf16_f32 v132, v22, v23
	v_cvt_pk_bf16_f32 v133, v24, v25
	ds_write_b128 v0, v[130:133] offset:13888
	v_cvt_pk_bf16_f32 v130, v10, v11
	v_cvt_pk_bf16_f32 v131, v12, v13
	v_cvt_pk_bf16_f32 v132, v14, v15
	v_cvt_pk_bf16_f32 v133, v16, v17
	ds_write_b128 v0, v[130:133] offset:16128
	v_cvt_pk_bf16_f32 v130, v2, v3
	v_cvt_pk_bf16_f32 v131, v4, v5
	v_cvt_pk_bf16_f32 v132, v6, v7
	v_cvt_pk_bf16_f32 v133, v8, v9
	ds_write_b128 v0, v[130:133] offset:16192
	v_and_b32_e32 v0, 0xffffff80, v136
	v_add_u32_e32 v130, s48, v0
	v_ashrrev_i32_e32 v131, 31, v130
	v_lshlrev_b64 v[130:131], 11, v[130:131]
	v_lshl_add_u64 v[130:131], s[38:39], 0, v[130:131]
	v_and_b32_e32 v0, 64, v136
	v_lshl_add_u64 v[130:131], s[46:47], 1, v[130:131]
	v_lshlrev_b32_e32 v0, 1, v0
	v_lshl_add_u64 v[138:139], v[130:131], 0, v[0:1]
	v_lshlrev_b32_e32 v0, 4, v136
	v_and_b32_e32 v0, 0x70, v0
	v_bfe_u32 v140, v136, 3, 3
	v_or_b32_e32 v130, v137, v0
	s_waitcnt lgkmcnt(0)
	v_mad_u32_u24 v137, v140, s4, v130
	ds_read_b128 v[66:69], v137
	ds_read_b128 v[70:73], v137 offset:1152
	ds_read_b128 v[74:77], v137 offset:2304
	ds_read_b128 v[78:81], v137 offset:3456
	ds_read_b128 v[82:85], v137 offset:4608
	ds_read_b128 v[86:89], v137 offset:5760
	ds_read_b128 v[90:93], v137 offset:6912
	ds_read_b128 v[94:97], v137 offset:8064
	ds_read_b128 v[98:101], v137 offset:9216
	ds_read_b128 v[102:105], v137 offset:10368
	ds_read_b128 v[106:109], v137 offset:11520
	ds_read_b128 v[110:113], v137 offset:12672
	ds_read_b128 v[114:117], v137 offset:13824
	ds_read_b128 v[118:121], v137 offset:14976
	ds_read_b128 v[122:125], v137 offset:16128
	ds_read_b128 v[126:129], v137 offset:17280
	v_lshl_add_u64 v[138:139], v[138:139], 0, v[0:1]
	v_lshlrev_b32_e32 v0, 11, v140
	v_lshl_add_u64 v[140:141], v[138:139], 0, v[0:1]
	s_mov_b64 s[50:51], 0
	s_waitcnt lgkmcnt(15)
	global_store_dwordx4 v[140:141], v[66:69], off
	v_or_b32_e32 v140, 0x4000, v0
	v_mov_b32_e32 v141, v1
	v_lshl_add_u64 v[140:141], v[138:139], 0, v[140:141]
	s_waitcnt lgkmcnt(14)
	global_store_dwordx4 v[140:141], v[70:73], off
	v_or_b32_e32 v140, 0x8000, v0
	v_mov_b32_e32 v141, v1
	v_lshl_add_u64 v[140:141], v[138:139], 0, v[140:141]
	s_waitcnt lgkmcnt(13)
	global_store_dwordx4 v[140:141], v[74:77], off
	v_or_b32_e32 v140, 0xc000, v0
	v_mov_b32_e32 v141, v1
	v_lshl_add_u64 v[140:141], v[138:139], 0, v[140:141]
	s_waitcnt lgkmcnt(12)
	global_store_dwordx4 v[140:141], v[78:81], off
	v_or_b32_e32 v140, 0x10000, v0
	v_mov_b32_e32 v141, v1
	v_lshl_add_u64 v[140:141], v[138:139], 0, v[140:141]
	s_waitcnt lgkmcnt(11)
	global_store_dwordx4 v[140:141], v[82:85], off
	v_or_b32_e32 v140, 0x14000, v0
	v_mov_b32_e32 v141, v1
	v_lshl_add_u64 v[140:141], v[138:139], 0, v[140:141]
	s_waitcnt lgkmcnt(10)
	global_store_dwordx4 v[140:141], v[86:89], off
	v_or_b32_e32 v140, 0x18000, v0
	v_mov_b32_e32 v141, v1
	v_lshl_add_u64 v[140:141], v[138:139], 0, v[140:141]
	s_waitcnt lgkmcnt(9)
	global_store_dwordx4 v[140:141], v[90:93], off
	v_or_b32_e32 v140, 0x1c000, v0
	v_mov_b32_e32 v141, v1
	v_lshl_add_u64 v[140:141], v[138:139], 0, v[140:141]
	s_waitcnt lgkmcnt(8)
	global_store_dwordx4 v[140:141], v[94:97], off
	v_or_b32_e32 v140, 0x20000, v0
	v_mov_b32_e32 v141, v1
	v_lshl_add_u64 v[140:141], v[138:139], 0, v[140:141]
	s_waitcnt lgkmcnt(7)
	global_store_dwordx4 v[140:141], v[98:101], off
	v_or_b32_e32 v140, 0x24000, v0
	v_mov_b32_e32 v141, v1
	v_lshl_add_u64 v[140:141], v[138:139], 0, v[140:141]
	s_waitcnt lgkmcnt(6)
	global_store_dwordx4 v[140:141], v[102:105], off
	v_or_b32_e32 v140, 0x28000, v0
	v_mov_b32_e32 v141, v1
	v_lshl_add_u64 v[140:141], v[138:139], 0, v[140:141]
	s_waitcnt lgkmcnt(5)
	global_store_dwordx4 v[140:141], v[106:109], off
	v_or_b32_e32 v140, 0x2c000, v0
	v_mov_b32_e32 v141, v1
	v_lshl_add_u64 v[140:141], v[138:139], 0, v[140:141]
	s_waitcnt lgkmcnt(4)
	global_store_dwordx4 v[140:141], v[110:113], off
	v_or_b32_e32 v140, 0x30000, v0
	v_mov_b32_e32 v141, v1
	v_lshl_add_u64 v[140:141], v[138:139], 0, v[140:141]
	s_waitcnt lgkmcnt(3)
	global_store_dwordx4 v[140:141], v[114:117], off
	v_or_b32_e32 v140, 0x34000, v0
	v_mov_b32_e32 v141, v1
	v_lshl_add_u64 v[140:141], v[138:139], 0, v[140:141]
	s_waitcnt lgkmcnt(2)
	global_store_dwordx4 v[140:141], v[118:121], off
	v_or_b32_e32 v140, 0x38000, v0
	v_mov_b32_e32 v141, v1
	v_lshl_add_u64 v[140:141], v[138:139], 0, v[140:141]
	v_or_b32_e32 v0, 0x3c000, v0
	s_waitcnt lgkmcnt(1)
	global_store_dwordx4 v[140:141], v[122:125], off
	v_lshl_add_u64 v[138:139], v[138:139], 0, v[0:1]
	s_waitcnt lgkmcnt(0)
	global_store_dwordx4 v[138:139], v[126:129], off
	s_waitcnt lgkmcnt(0)
	s_barrier
